# last layer: skip the meta-row skinny GEMMs after the mixers (their rows are dropped from the output), on top of 64-bit accumulator zeroing
# speedup vs baseline: 1.0141x; 1.0070x over previous
; #define LAS __attribute__((address_space(3)))
; template <class SE> __device__ __forceinline__ void skinny_gemm(const Frame& F, const bf16* Am, const bf16* Bt, int ntiles, int K, const SE& E) {
;     const int j = F.lane & 15, g = F.lane >> 4, w = F.wave;
;     const int nsteps = K / 32, sb = (nsteps * w) / 8, se = (nsteps * (w + 1)) / 8;
;     LAS f32x4* part = (LAS f32x4*)F.lds;
;     for (int tile = F.bx; tile < ntiles; tile += F.G) {
;         const bf16* ap = Am + (size_t)j * K + 8 * g;
;         const bf16* b0 = Bt + (size_t)(E.brow(tile, 0) + j) * K + 8 * g;
;         const bf16* b1 = Bt + (size_t)(E.brow(tile, 1) + j) * K + 8 * g;
;         f32x4 acc0 = {0.f, 0.f, 0.f, 0.f}, acc1 = {0.f, 0.f, 0.f, 0.f};
; __global__ void __launch_bounds__(NTHREADS, 2) fwd_megakernel(Params p) {
;     ...
;               SkGate<false> SE{E.G, nullptr, E.O}; skinny_gemm(F, (const bf16*)(ws + WS_YR) + (size_t)MF * D, (const bf16*)(ws + WS_WBRR), D / 16, D, SE); }
.LBB0_574:
	s_and_b32 s0, s37, 0xffffffc0
	s_ashr_i32 s40, s37, 6
	s_add_i32 s0, s0, 64
	v_and_b32_e32 v0, 63, v146
	s_lshl_b32 s38, s40, 3
	s_ashr_i32 s39, s0, 3
	v_and_b32_e32 v150, 15, v146
	s_cmpk_lt_i32 s36, 0x80
	v_lshrrev_b32_e32 v1, 2, v0
	v_lshlrev_b32_e32 v153, 4, v0
	s_cselect_b64 s[6:7], -1, 0
	s_cmpk_gt_i32 s36, 0x7f
	v_lshlrev_b32_e32 v152, 11, v150
	v_lshlrev_b32_e32 v132, 12, v150
	v_and_b32_e32 v130, 48, v0
	v_and_b32_e32 v154, 12, v1
	v_add_u32_e32 v151, 0, v153
	s_cbranch_scc1 .LBB0_615
	v_readlane_b32 s98, v255, 52
	s_cmp_eq_u32 s98, 0
	s_cbranch_scc1 .LBB0_615
	v_mov_b32_e32 v133, v97
	v_lshl_add_u64 v[0:1], s[4:5], 0, v[132:133]
	v_mov_b32_e32 v131, v97
	v_lshl_add_u64 v[0:1], v[0:1], 0, v[130:131]
	s_mov_b64 s[0:1], 0x34780000
	s_cmp_gt_i32 s39, s38
	v_lshl_add_u64 v[68:69], v[0:1], 0, s[0:1]
	v_lshl_add_u64 v[70:71], s[10:11], 0, v[130:131]
	s_cselect_b64 s[0:1], -1, 0
	s_lshl_b32 s10, s40, 10
	s_add_i32 s14, s10, 0
	s_cmp_lt_u32 s37, 64
	s_brev_b32 s15, 64
	v_mov_b32_e32 v0, 0
	s_cselect_b64 s[10:11], -1, 0
	v_or3_b32 v72, v154, v152, s15
	v_mov_b32_e32 v73, v97
	v_add_u32_e32 v76, s14, v153
	s_lshl_b32 s41, s40, 8
	s_sub_i32 s42, s39, s38
	s_mov_b32 s43, s36
	v_mov_b32_e32 v1, v0
	v_mov_b32_e32 v2, v0
	v_mov_b32_e32 v3, v0
	v_mov_b32_e32 v36, v0
	v_mov_b32_e32 v37, v0
	v_mov_b32_e32 v38, v0
	v_mov_b32_e32 v39, v0
	v_mov_b32_e32 v40, v0
	v_mov_b32_e32 v41, v0
	v_mov_b32_e32 v42, v0
	v_mov_b32_e32 v43, v0
	v_mov_b32_e32 v44, v0
	v_mov_b32_e32 v45, v0
	v_mov_b32_e32 v46, v0
	v_mov_b32_e32 v47, v0
	v_mov_b32_e32 v48, v0
	v_mov_b32_e32 v49, v0
	v_mov_b32_e32 v50, v0
	v_mov_b32_e32 v51, v0
	v_mov_b32_e32 v52, v0
	v_mov_b32_e32 v53, v0
	v_mov_b32_e32 v54, v0
	v_mov_b32_e32 v55, v0
	v_mov_b32_e32 v56, v0
	v_mov_b32_e32 v57, v0
	v_mov_b32_e32 v58, v0
	v_mov_b32_e32 v59, v0
	v_mov_b32_e32 v60, v0
	v_mov_b32_e32 v61, v0
	v_mov_b32_e32 v62, v0
	v_mov_b32_e32 v63, v0
	s_branch .LBB0_577

; #define LAS __attribute__((address_space(3)))
; template <class SE> __device__ __forceinline__ void skinny_gemm(const Frame& F, const bf16* Am, const bf16* Bt, int ntiles, int K, const SE& E) {
;     const int j = F.lane & 15, g = F.lane >> 4, w = F.wave;
;     const int nsteps = K / 32, sb = (nsteps * w) / 8, se = (nsteps * (w + 1)) / 8;
;     LAS f32x4* part = (LAS f32x4*)F.lds;
;     for (int tile = F.bx; tile < ntiles; tile += F.G) {
;         const bf16* ap = Am + (size_t)j * K + 8 * g;
;         const bf16* b0 = Bt + (size_t)(E.brow(tile, 0) + j) * K + 8 * g;
;         const bf16* b1 = Bt + (size_t)(E.brow(tile, 1) + j) * K + 8 * g;
;         f32x4 acc0 = {0.f, 0.f, 0.f, 0.f}, acc1 = {0.f, 0.f, 0.f, 0.f};
; __global__ void __launch_bounds__(NTHREADS, 2) fwd_megakernel(Params p) {
;     ...
;               SkGate<true> SE{E.G, E.T, E.O}; skinny_gemm(F, (const bf16*)(ws + WS_YH) + (size_t)MF * D, (const bf16*)(ws + WS_WBRH), D / 16, D, SE); }
.LBB0_639:
	s_andn2_b64 vcc, exec, s[6:7]
	s_cbranch_vccnz .LBB0_680
	v_readlane_b32 s98, v255, 52
	s_cmp_eq_u32 s98, 0
	s_cbranch_scc1 .LBB0_680
	v_mov_b32_e32 v133, v97
	s_waitcnt vmcnt(1)
	v_lshl_add_u64 v[0:1], s[4:5], 0, v[132:133]
	v_mov_b32_e32 v131, v97
	v_lshl_add_u64 v[0:1], v[0:1], 0, v[130:131]
	s_mov_b64 s[0:1], 0x38880000
	s_cmp_gt_i32 s39, s38
	v_lshl_add_u64 v[68:69], v[0:1], 0, s[0:1]
	s_cselect_b64 s[0:1], -1, 0
	s_lshl_b32 s4, s40, 10
	s_add_i32 s6, s4, 0
	s_cmp_lt_u32 s37, 64
	s_brev_b32 s7, 64
	v_mov_b32_e32 v0, 0
	v_lshl_add_u64 v[70:71], s[14:15], 0, v[130:131]
	s_cselect_b64 s[4:5], -1, 0
	v_or3_b32 v72, v154, v152, s7
	v_mov_b32_e32 v73, v97
	v_add_u32_e32 v76, s6, v153
	s_lshl_b32 s30, s40, 8
	s_sub_i32 s31, s39, s38
	v_mov_b32_e32 v1, v0
	v_mov_b32_e32 v2, v0
	v_mov_b32_e32 v3, v0
	v_mov_b32_e32 v36, v0
	v_mov_b32_e32 v37, v0
	v_mov_b32_e32 v38, v0
	v_mov_b32_e32 v39, v0
	v_mov_b32_e32 v40, v0
	v_mov_b32_e32 v41, v0
	v_mov_b32_e32 v42, v0
	v_mov_b32_e32 v43, v0
	v_mov_b32_e32 v44, v0
	v_mov_b32_e32 v45, v0
	v_mov_b32_e32 v46, v0
	v_mov_b32_e32 v47, v0
	v_mov_b32_e32 v48, v0
	v_mov_b32_e32 v49, v0
	v_mov_b32_e32 v50, v0
	v_mov_b32_e32 v51, v0
	v_mov_b32_e32 v52, v0
	v_mov_b32_e32 v53, v0
	v_mov_b32_e32 v54, v0
	v_mov_b32_e32 v55, v0
	v_mov_b32_e32 v56, v0
	v_mov_b32_e32 v57, v0
	v_mov_b32_e32 v58, v0
	v_mov_b32_e32 v59, v0
	v_mov_b32_e32 v60, v0
	v_mov_b32_e32 v61, v0
	v_mov_b32_e32 v62, v0
	v_mov_b32_e32 v63, v0
	s_branch .LBB0_642

; #define LAS __attribute__((address_space(3)))
; template <class SE> __device__ __forceinline__ void skinny_gemm(const Frame& F, const bf16* Am, const bf16* Bt, int ntiles, int K, const SE& E) {
;     const int j = F.lane & 15, g = F.lane >> 4, w = F.wave;
;     const int nsteps = K / 32, sb = (nsteps * w) / 8, se = (nsteps * (w + 1)) / 8;
;     LAS f32x4* part = (LAS f32x4*)F.lds;
;     for (int tile = F.bx; tile < ntiles; tile += F.G) {
;         const bf16* ap = Am + (size_t)j * K + 8 * g;
;         const bf16* b0 = Bt + (size_t)(E.brow(tile, 0) + j) * K + 8 * g;
;         const bf16* b1 = Bt + (size_t)(E.brow(tile, 1) + j) * K + 8 * g;
;         f32x4 acc0 = {0.f, 0.f, 0.f, 0.f}, acc1 = {0.f, 0.f, 0.f, 0.f};
; __global__ void __launch_bounds__(NTHREADS, 2) fwd_megakernel(Params p) {
;     ...
;             { SkF32 SE{E.O}; skinny_gemm(F, (const bf16*)(ws + WS_Y) + (size_t)MF * D, (const bf16*)(ws + WS_WOUT), D / 16, D, SE); }
.LBB0_756:
	s_cmpk_gt_i32 s28, 0x7f
	s_cbranch_scc1 .LBB0_797
	v_readlane_b32 s98, v255, 52
	s_cmp_eq_u32 s98, 0
	s_cbranch_scc1 .LBB0_797
	v_and_b32_e32 v76, 15, v140
	s_and_b32 s0, s29, 0xffffffc0
	s_ashr_i32 s8, s29, 3
	s_add_i32 s0, s0, 64
	v_lshlrev_b32_e32 v96, 12, v76
	s_and_b32 s24, s8, -8
	s_ashr_i32 s25, s0, 3
	v_lshl_add_u64 v[0:1], s[6:7], 0, v[96:97]
	v_and_b32_e32 v4, 48, v140
	v_mov_b32_e32 v5, v97
	v_lshrrev_b32_e32 v2, 1, v140
	v_lshl_add_u64 v[0:1], v[0:1], 0, v[4:5]
	s_mov_b64 s[0:1], 0x28480000
	s_cmp_gt_i32 s25, s24
	v_and_b32_e32 v2, 24, v2
	v_mov_b32_e32 v3, v97
	v_lshl_add_u64 v[68:69], v[0:1], 0, s[0:1]
	v_lshl_add_u64 v[70:71], s[2:3], 0, v[4:5]
	s_cselect_b64 s[0:1], -1, 0
	s_lshl_b32 s2, s29, 4
	v_lshl_add_u64 v[0:1], s[4:5], 0, v[96:97]
	s_and_b32 s2, s2, 0xfffffc00
	v_lshl_add_u64 v[0:1], v[0:1], 0, v[2:3]
	s_mov_b64 s[4:5], 0x4000000
	s_add_i32 s6, s2, 0
	v_lshl_add_u64 v[72:73], v[0:1], 0, s[4:5]
	v_lshlrev_b32_e32 v0, 4, v140
	s_cmp_lt_u32 s29, 64
	v_and_b32_e32 v0, 0x3f0, v0
	s_cselect_b64 s[2:3], -1, 0
	v_add_u32_e32 v77, s6, v0
	v_add_u32_e32 v78, 0, v0
	s_lshl_b32 s4, s8, 5
	v_mov_b32_e32 v0, 0
	s_and_b32 s26, s4, 0xffffff00
	s_sub_i32 s27, s25, s24
	v_mov_b32_e32 v1, v0
	v_mov_b32_e32 v2, v0
	v_mov_b32_e32 v3, v0
	v_mov_b32_e32 v36, v0
	v_mov_b32_e32 v37, v0
	v_mov_b32_e32 v38, v0
	v_mov_b32_e32 v39, v0
	v_mov_b32_e32 v40, v0
	v_mov_b32_e32 v41, v0
	v_mov_b32_e32 v42, v0
	v_mov_b32_e32 v43, v0
	v_mov_b32_e32 v44, v0
	v_mov_b32_e32 v45, v0
	v_mov_b32_e32 v46, v0
	v_mov_b32_e32 v47, v0
	v_mov_b32_e32 v48, v0
	v_mov_b32_e32 v49, v0
	v_mov_b32_e32 v50, v0
	v_mov_b32_e32 v51, v0
	v_mov_b32_e32 v52, v0
	v_mov_b32_e32 v53, v0
	v_mov_b32_e32 v54, v0
	v_mov_b32_e32 v55, v0
	v_mov_b32_e32 v56, v0
	v_mov_b32_e32 v57, v0
	v_mov_b32_e32 v58, v0
	v_mov_b32_e32 v59, v0
	v_mov_b32_e32 v60, v0
	v_mov_b32_e32 v61, v0
	v_mov_b32_e32 v62, v0
	v_mov_b32_e32 v63, v0
	s_branch .LBB0_759

; #define LAS __attribute__((address_space(3)))
; template <class SE> __device__ __forceinline__ void skinny_gemm(const Frame& F, const bf16* Am, const bf16* Bt, int ntiles, int K, const SE& E) {
;     const int j = F.lane & 15, g = F.lane >> 4, w = F.wave;
;     const int nsteps = K / 32, sb = (nsteps * w) / 8, se = (nsteps * (w + 1)) / 8;
;     LAS f32x4* part = (LAS f32x4*)F.lds;
;     for (int tile = F.bx; tile < ntiles; tile += F.G) {
;         const bf16* ap = Am + (size_t)j * K + 8 * g;
;         const bf16* b0 = Bt + (size_t)(E.brow(tile, 0) + j) * K + 8 * g;
;         const bf16* b1 = Bt + (size_t)(E.brow(tile, 1) + j) * K + 8 * g;
;         f32x4 acc0 = {0.f, 0.f, 0.f, 0.f}, acc1 = {0.f, 0.f, 0.f, 0.f};
; __global__ void __launch_bounds__(NTHREADS, 2) fwd_megakernel(Params p) {
;     ...
;             { SkSwiglu SE{E.O}; skinny_gemm(F, A + (size_t)MF * D, (const bf16*)(ws + WS_WGU), DFF / 16, D, SE); }
.LBB0_986:
	s_cmpk_gt_i32 s30, 0x15f
	s_cbranch_scc1 .LBB0_1027
	v_readlane_b32 s98, v255, 52
	s_cmp_eq_u32 s98, 0
	s_cbranch_scc1 .LBB0_1027
	v_and_b32_e32 v118, 15, v142
	s_and_b32 s11, s31, 0xffffffc0
	v_lshlrev_b32_e32 v96, 12, v118
	v_lshrrev_b32_e32 v2, 1, v142
	s_add_i32 s0, s11, 64
	v_lshl_add_u64 v[0:1], s[8:9], 0, v[96:97]
	v_and_b32_e32 v96, 24, v2
	v_and_b32_e32 v2, 48, v142
	v_mov_b32_e32 v3, v97
	s_ashr_i32 s27, s0, 3
	v_lshl_add_u64 v[0:1], v[0:1], 0, v[2:3]
	s_mov_b64 s[0:1], 0xde00000
	s_ashr_i32 s10, s31, 3
	v_lshl_add_u64 v[108:109], v[0:1], 0, s[0:1]
	v_mul_u32_u24_e32 v0, 0x1600, v118
	s_and_b32 s26, s10, -8
	v_lshlrev_b32_e32 v0, 1, v0
	v_mov_b32_e32 v1, v97
	s_cmp_gt_i32 s27, s26
	v_lshl_add_u64 v[0:1], s[2:3], 0, v[0:1]
	v_lshl_add_u64 v[110:111], s[6:7], 0, v[2:3]
	s_cselect_b64 s[0:1], -1, 0
	s_lshl_b32 s6, s11, 4
	v_lshl_add_u64 v[0:1], v[0:1], 0, v[96:97]
	s_mov_b64 s[2:3], 0xb000000
	s_add_i32 s8, s6, 0
	v_lshl_add_u64 v[112:113], v[0:1], 0, s[2:3]
	v_lshlrev_b32_e32 v0, 4, v142
	s_cmp_lt_u32 s31, 64
	v_and_b32_e32 v0, 0x3f0, v0
	s_cselect_b64 s[6:7], -1, 0
	v_add_u32_e32 v119, s8, v0
	v_add_u32_e32 v120, 0, v0
	s_lshl_b32 s2, s10, 5
	v_mov_b32_e32 v0, 0
	s_and_b32 s28, s2, 0xffffff00
	s_sub_i32 s29, s27, s26
	v_mov_b32_e32 v1, v0
	v_mov_b32_e32 v2, v0
	v_mov_b32_e32 v3, v0
	v_mov_b32_e32 v68, v0
	v_mov_b32_e32 v69, v0
	v_mov_b32_e32 v70, v0
	v_mov_b32_e32 v71, v0
	v_mov_b32_e32 v72, v0
	v_mov_b32_e32 v73, v0
	v_mov_b32_e32 v74, v0
	v_mov_b32_e32 v75, v0
	v_mov_b32_e32 v76, v0
	v_mov_b32_e32 v77, v0
	v_mov_b32_e32 v78, v0
	v_mov_b32_e32 v79, v0
	v_mov_b32_e32 v80, v0
	v_mov_b32_e32 v81, v0
	v_mov_b32_e32 v82, v0
	v_mov_b32_e32 v83, v0
	v_mov_b32_e32 v84, v0
	v_mov_b32_e32 v85, v0
	v_mov_b32_e32 v86, v0
	v_mov_b32_e32 v87, v0
	v_mov_b32_e32 v88, v0
	v_mov_b32_e32 v89, v0
	v_mov_b32_e32 v90, v0
	v_mov_b32_e32 v91, v0
	v_mov_b32_e32 v92, v0
	v_mov_b32_e32 v93, v0
	v_mov_b32_e32 v94, v0
	v_mov_b32_e32 v95, v0
	s_branch .LBB0_989

; #define LAS __attribute__((address_space(3)))
; template <class SE> __device__ __forceinline__ void skinny_gemm(const Frame& F, const bf16* Am, const bf16* Bt, int ntiles, int K, const SE& E) {
;     const int j = F.lane & 15, g = F.lane >> 4, w = F.wave;
;     const int nsteps = K / 32, sb = (nsteps * w) / 8, se = (nsteps * (w + 1)) / 8;
;     LAS f32x4* part = (LAS f32x4*)F.lds;
;     for (int tile = F.bx; tile < ntiles; tile += F.G) {
;         const bf16* ap = Am + (size_t)j * K + 8 * g;
;         const bf16* b0 = Bt + (size_t)(E.brow(tile, 0) + j) * K + 8 * g;
;         const bf16* b1 = Bt + (size_t)(E.brow(tile, 1) + j) * K + 8 * g;
;         f32x4 acc0 = {0.f, 0.f, 0.f, 0.f}, acc1 = {0.f, 0.f, 0.f, 0.f};
; __global__ void __launch_bounds__(NTHREADS, 2) fwd_megakernel(Params p) {
;     ...
;             { SkF32 SE{E.O}; skinny_gemm(F, (const bf16*)(ws + WS_HID) + (size_t)MF * DFF, (const bf16*)(ws + WS_WD), D / 16, DFF, SE); }
.LBB0_1107:
	s_cmpk_gt_i32 s26, 0x7f
	s_cbranch_scc1 .LBB0_1149
	v_readlane_b32 s98, v255, 52
	s_cmp_eq_u32 s98, 0
	s_cbranch_scc1 .LBB0_1149
	v_and_b32_e32 v76, 15, v140
	s_ashr_i32 s12, s29, 6
	v_mul_u32_u24_e32 v0, 0x1600, v76
	s_mul_i32 s0, s12, 0xb0
	v_lshlrev_b32_e32 v96, 1, v0
	v_lshrrev_b32_e32 v2, 1, v140
	s_addk_i32 s0, 0xb0
	v_lshl_add_u64 v[0:1], s[10:11], 0, v[96:97]
	v_and_b32_e32 v96, 24, v2
	v_and_b32_e32 v2, 48, v140
	v_mov_b32_e32 v3, v97
	s_ashr_i32 s28, s0, 3
	v_lshl_add_u64 v[0:1], v[0:1], 0, v[2:3]
	s_mov_b64 s[0:1], 0x18f00000
	v_lshl_add_u64 v[68:69], v[0:1], 0, s[0:1]
	v_lshlrev_b32_e32 v0, 12, v76
	v_mov_b32_e32 v1, v97
	s_mul_i32 s27, s12, 22
	v_lshl_add_u64 v[0:1], s[6:7], 0, v[0:1]
	s_cmp_gt_i32 s28, s27
	v_lshl_add_u64 v[0:1], v[0:1], 0, v[96:97]
	s_mov_b64 s[6:7], 0x4000000
	s_cselect_b64 s[0:1], -1, 0
	s_lshl_b32 s2, s12, 10
	v_lshl_add_u64 v[72:73], v[0:1], 0, s[6:7]
	v_lshlrev_b32_e32 v0, 4, v140
	v_lshl_add_u64 v[70:71], s[8:9], 0, v[2:3]
	s_add_i32 s8, s2, 0
	v_and_b32_e32 v0, 0x3f0, v0
	s_cmp_lt_u32 s29, 64
	v_add_u32_e32 v77, s8, v0
	v_add_u32_e32 v78, 0, v0
	v_mov_b32_e32 v0, 0
	s_cselect_b64 s[2:3], -1, 0
	s_mul_i32 s29, s12, 0x2c0
	s_sub_i32 s30, s28, s27
	v_mov_b32_e32 v1, v0
	v_mov_b32_e32 v2, v0
	v_mov_b32_e32 v3, v0
	v_mov_b32_e32 v36, v0
	v_mov_b32_e32 v37, v0
	v_mov_b32_e32 v38, v0
	v_mov_b32_e32 v39, v0
	v_mov_b32_e32 v40, v0
	v_mov_b32_e32 v41, v0
	v_mov_b32_e32 v42, v0
	v_mov_b32_e32 v43, v0
	v_mov_b32_e32 v44, v0
	v_mov_b32_e32 v45, v0
	v_mov_b32_e32 v46, v0
	v_mov_b32_e32 v47, v0
	v_mov_b32_e32 v48, v0
	v_mov_b32_e32 v49, v0
	v_mov_b32_e32 v50, v0
	v_mov_b32_e32 v51, v0
	v_mov_b32_e32 v52, v0
	v_mov_b32_e32 v53, v0
	v_mov_b32_e32 v54, v0
	v_mov_b32_e32 v55, v0
	v_mov_b32_e32 v56, v0
	v_mov_b32_e32 v57, v0
	v_mov_b32_e32 v58, v0
	v_mov_b32_e32 v59, v0
	v_mov_b32_e32 v60, v0
	v_mov_b32_e32 v61, v0
	v_mov_b32_e32 v62, v0
	v_mov_b32_e32 v63, v0
	s_branch .LBB0_1110
